# LayerNorm phases: gamma/beta hoisted out of the row loop into registers (no per-chunk reload + vmcnt(0) drain); on top of ping-pong attention w/ accumulator-init softmax and P10 batched epilogue
# baseline (speedup 1.0000x reference)
.LBB0_1421:
	s_or_b64 exec, exec, s[4:5]
	v_readlane_b32 s0, v254, 0
	s_lshl_b32 s64, s0, 3
	v_lshl_add_u32 v128, s2, 3, v218
	s_movk_i32 s0, 0x4000
	v_cmp_gt_i32_e64 s[4:5], s0, v128
	v_mbcnt_lo_u32_b32 v152, -1, 0
	s_waitcnt lgkmcnt(0)
	s_barrier
	v_readlane_b32 s1, v254, 1
	s_and_saveexec_b64 s[12:13], s[4:5]
	s_cbranch_execz .LBB0_1426
	v_mbcnt_hi_u32_b32 v1, -1, v152
	v_and_b32_e32 v3, 64, v1
	v_xor_b32_e32 v2, 1, v1
	v_add_u32_e32 v3, 64, v3
	v_cmp_lt_i32_e32 vcc, v2, v3
	v_readlane_b32 s6, v254, 3
	v_readlane_b32 s7, v254, 4
	v_cndmask_b32_e32 v2, v1, v2, vcc
	v_lshlrev_b32_e32 v90, 2, v2
	v_xor_b32_e32 v2, 2, v1
	v_cmp_lt_i32_e32 vcc, v2, v3
	s_load_dwordx4 s[8:11], s[6:7], 0x88
	s_load_dwordx2 s[16:17], s[6:7], 0xc0
	v_cndmask_b32_e32 v2, v1, v2, vcc
	v_lshlrev_b32_e32 v91, 2, v2
	v_xor_b32_e32 v2, 4, v1
	v_cmp_lt_i32_e32 vcc, v2, v3
	v_and_b32_e32 v0, 0xfc, v212
	v_mov_b32_e32 v55, 0
	v_cndmask_b32_e32 v2, v1, v2, vcc
	v_lshlrev_b32_e32 v92, 2, v2
	v_xor_b32_e32 v2, 8, v1
	v_cmp_lt_i32_e32 vcc, v2, v3
	v_lshlrev_b32_e32 v54, 2, v0
	s_waitcnt lgkmcnt(0)
	v_lshl_add_u64 v[56:57], s[8:9], 0, v[54:55]
	v_cndmask_b32_e32 v2, v1, v2, vcc
	v_lshlrev_b32_e32 v93, 2, v2
	v_xor_b32_e32 v2, 16, v1
	v_cmp_lt_i32_e32 vcc, v2, v3
	v_lshl_add_u64 v[58:59], s[10:11], 0, v[54:55]
	v_or_b32_e32 v4, 0x500, v0
	v_cndmask_b32_e32 v2, v1, v2, vcc
	v_lshlrev_b32_e32 v94, 2, v2
	v_xor_b32_e32 v2, 32, v1
	v_cmp_lt_i32_e32 vcc, v2, v3
	v_or_b32_e32 v6, 0x600, v0
	v_or_b32_e32 v8, 0x700, v0
	v_cndmask_b32_e32 v1, v1, v2, vcc
	v_or_b32_e32 v2, 0x400, v0
	v_lshlrev_b32_e32 v54, 2, v2
	v_lshl_add_u64 v[60:61], s[8:9], 0, v[54:55]
	v_lshl_add_u64 v[62:63], s[10:11], 0, v[54:55]
	v_lshlrev_b32_e32 v54, 2, v4
	v_lshl_add_u64 v[64:65], s[8:9], 0, v[54:55]
	v_lshl_add_u64 v[66:67], s[10:11], 0, v[54:55]
	v_lshlrev_b32_e32 v54, 2, v6
	v_readlane_b32 s6, v254, 0
	v_lshl_add_u64 v[68:69], s[8:9], 0, v[54:55]
	v_lshl_add_u64 v[70:71], s[10:11], 0, v[54:55]
	v_lshlrev_b32_e32 v54, 2, v8
	v_readlane_b32 s7, v254, 1
	v_ashrrev_i32_e32 v129, 31, v128
	v_lshl_add_u64 v[74:75], s[10:11], 0, v[54:55]
	s_lshl_b32 s10, s6, 4
	v_lshlrev_b64 v[10:11], 12, v[128:129]
	v_readlane_b32 s6, v254, 14
	v_lshl_or_b32 v10, v217, 3, v10
	v_readlane_b32 s7, v254, 15
	v_lshl_add_u64 v[72:73], s[8:9], 0, v[54:55]
	v_lshlrev_b32_e32 v54, 1, v0
	v_lshl_add_u64 v[10:11], s[6:7], 0, v[10:11]
	s_mov_b64 s[6:7], 0x8e00000
	v_lshl_add_u64 v[78:79], v[10:11], 0, s[6:7]
	v_lshlrev_b64 v[10:11], 13, v[128:129]
	v_lshl_or_b32 v10, v217, 4, v10
	s_ashr_i32 s11, s10, 31
	v_lshl_add_u64 v[10:11], s[16:17], 0, v[10:11]
	s_mov_b64 s[6:7], 0x1000
	v_lshlrev_b32_e32 v95, 2, v1
	v_lshl_add_u64 v[76:77], s[40:41], 0, v[54:55]
	s_lshl_b64 s[18:19], s[10:11], 12
	v_lshl_add_u64 v[80:81], v[10:11], 0, s[6:7]
	s_lshl_b64 s[20:21], s[10:11], 13
	s_mov_b64 s[22:23], 0
	v_lshlrev_b32_e32 v54, 2, v0
	v_lshlrev_b32_e32 v82, 2, v2
	v_lshlrev_b32_e32 v84, 2, v4
	v_lshlrev_b32_e32 v86, 2, v6
	v_lshlrev_b32_e32 v88, 2, v8
	v_mov_b32_e32 v96, 0x3727c5ac
	s_mov_b32 s1, 0x800000
	s_movk_i32 s3, 0x3fff
	v_mov_b32_e32 v97, v128
	global_load_dwordx4 v[132:135], v[56:57], off
	global_load_dwordx4 v[136:139], v[58:59], off
	global_load_dwordx4 v[140:143], v[56:57], off offset:1024
	global_load_dwordx4 v[144:147], v[58:59], off offset:1024
	global_load_dwordx4 v[148:151], v[56:57], off offset:2048
	global_load_dwordx4 v[156:159], v[58:59], off offset:2048
	global_load_dwordx4 v[160:163], v[56:57], off offset:3072
	global_load_dwordx4 v[164:167], v[58:59], off offset:3072
	global_load_dwordx4 v[168:171], v[60:61], off
	global_load_dwordx4 v[172:175], v[62:63], off
	global_load_dwordx4 v[176:179], v[64:65], off
	global_load_dwordx4 v[180:183], v[66:67], off
	global_load_dwordx4 v[184:187], v[68:69], off
	global_load_dwordx4 v[188:191], v[70:71], off
	global_load_dwordx4 v[192:195], v[72:73], off
	global_load_dwordx4 v[196:199], v[74:75], off
	s_waitcnt vmcnt(0)
	s_branch .LBB0_1424

.LBB0_1424:
	global_load_dwordx4 v[46:49], v[80:81], off offset:-3072 nt
	global_load_dwordx4 v[50:53], v[80:81], off offset:-4096 nt
	global_load_dwordx4 v[42:45], v[80:81], off offset:-2048 nt
	global_load_dwordx4 v[38:41], v[80:81], off offset:-1024 nt
	global_load_dwordx4 v[34:37], v[80:81], off nt
	global_load_dwordx4 v[22:25], v[80:81], off offset:1024 nt
	global_load_dwordx4 v[16:19], v[80:81], off offset:2048 nt
	global_load_dwordx4 v[12:15], v[80:81], off offset:3072 nt
	v_mov_b32_e32 v83, v55
	v_mov_b32_e32 v85, v55
	v_mov_b32_e32 v87, v55
	v_mov_b32_e32 v89, v55
	s_waitcnt vmcnt(7)
	v_mov_b32_e32 v0, v46
	s_waitcnt vmcnt(6)
	v_mov_b32_e32 v1, v50
	v_mov_b32_e32 v2, v47
	v_mov_b32_e32 v3, v51
	v_mov_b32_e32 v4, v48
	v_mov_b32_e32 v5, v52
	v_mov_b32_e32 v6, v49
	v_mov_b32_e32 v7, v53
	s_waitcnt vmcnt(5)
	v_mov_b32_e32 v8, v43
	v_mov_b32_e32 v9, v44
	v_mov_b32_e32 v10, v42
	v_mov_b32_e32 v11, v45
	v_pk_add_f32 v[0:1], v[0:1], v[2:3]
	v_pk_add_f32 v[2:3], v[4:5], v[6:7]
	v_pk_add_f32 v[4:5], v[8:9], v[10:11]
	v_pk_add_f32 v[0:1], v[0:1], v[2:3]
	v_pk_add_f32 v[2:3], v[4:5], v[4:5] op_sel_hi:[0,1]
	v_add_f32_e32 v1, 0, v1
	s_waitcnt vmcnt(4)
	v_add_f32_e32 v21, v38, v39
	v_add_f32_e32 v27, v40, v41
	s_waitcnt vmcnt(3)
	v_mov_b32_e32 v20, v34
	v_mov_b32_e32 v26, v35
	v_mov_b32_e32 v28, v37
	v_mov_b32_e32 v2, v36
	v_add_f32_e32 v29, v0, v1
	s_waitcnt vmcnt(2)
	v_mov_b32_e32 v30, v23
	v_mov_b32_e32 v31, v24
	v_mov_b32_e32 v32, v22
	v_mov_b32_e32 v33, v25
	v_pk_add_f32 v[6:7], v[20:21], v[26:27]
	v_pk_add_f32 v[0:1], v[2:3], v[28:29]
	v_pk_add_f32 v[8:9], v[30:31], v[32:33]
	v_pk_add_f32 v[0:1], v[6:7], v[0:1]
	v_pk_add_f32 v[4:5], v[8:9], v[8:9] op_sel_hi:[0,1]
	v_pk_add_f32 v[0:1], v[0:1], v[0:1] op_sel_hi:[0,1]
	s_waitcnt vmcnt(1)
	v_add_f32_e32 v99, v16, v17
	v_add_f32_e32 v101, v18, v19
	s_waitcnt vmcnt(0)
	v_mov_b32_e32 v98, v12
	v_mov_b32_e32 v100, v13
	v_mov_b32_e32 v4, v14
	v_mov_b32_e32 v0, v15
	v_pk_add_f32 v[10:11], v[98:99], v[100:101]
	v_pk_add_f32 v[0:1], v[4:5], v[0:1]
	v_mov_b64_e32 v[98:99], v[132:133]
	v_mov_b64_e32 v[100:101], v[134:135]
	v_mov_b64_e32 v[102:103], v[136:137]
	v_mov_b64_e32 v[104:105], v[138:139]
	v_pk_add_f32 v[0:1], v[10:11], v[0:1]
	s_nop 0
	v_add_f32_e32 v0, v0, v1
	ds_bpermute_b32 v1, v90, v0
	s_waitcnt lgkmcnt(0)
	v_add_f32_e32 v0, v0, v1
	ds_bpermute_b32 v1, v91, v0
	s_waitcnt lgkmcnt(0)
	v_add_f32_e32 v0, v0, v1
	ds_bpermute_b32 v1, v92, v0
	s_waitcnt lgkmcnt(0)
	v_add_f32_e32 v0, v0, v1
	ds_bpermute_b32 v1, v93, v0
	s_waitcnt lgkmcnt(0)
	v_add_f32_e32 v0, v0, v1
	ds_bpermute_b32 v1, v94, v0
	s_waitcnt lgkmcnt(0)
	v_add_f32_e32 v0, v0, v1
	ds_bpermute_b32 v1, v95, v0
	s_waitcnt lgkmcnt(0)
	v_add_f32_e32 v31, v0, v1
	v_fmamk_f32 v53, v31, 0xba000000, v53
	v_fmamk_f32 v51, v31, 0xba000000, v51
	v_fmamk_f32 v107, v31, 0xba000000, v49
	v_fmamk_f32 v47, v31, 0xba000000, v47
	v_fmamk_f32 v52, v31, 0xba000000, v52
	v_fmac_f32_e32 v50, 0xba000000, v31
	v_fmamk_f32 v106, v31, 0xba000000, v48
	v_fmac_f32_e32 v46, 0xba000000, v31
	v_fmamk_f32 v109, v31, 0xba000000, v43
	v_fmamk_f32 v108, v31, 0xba000000, v42
	v_fmamk_f32 v45, v31, 0xba000000, v45
	v_fmac_f32_e32 v44, 0xba000000, v31
	v_mov_b32_e32 v2, v51
	v_mov_b32_e32 v3, v47
	v_mov_b32_e32 v6, v53
	v_mov_b32_e32 v7, v107
	v_mov_b32_e32 v0, v50
	v_mov_b32_e32 v1, v46
	v_mov_b32_e32 v4, v52
	v_mov_b32_e32 v5, v106
	v_pk_mul_f32 v[8:9], v[44:45], v[44:45]
	v_pk_mul_f32 v[10:11], v[108:109], v[108:109]
	v_pk_mul_f32 v[2:3], v[2:3], v[2:3]
	v_pk_mul_f32 v[6:7], v[6:7], v[6:7]
	v_fmamk_f32 v110, v31, 0xba000000, v38
	v_fmac_f32_e32 v40, 0xba000000, v31
	v_pk_mov_b32 v[32:33], v[10:11], v[8:9] op_sel:[1,0]
	v_mov_b32_e32 v11, v9
	v_pk_fma_f32 v[0:1], v[0:1], v[0:1], v[2:3]
	v_pk_fma_f32 v[2:3], v[4:5], v[4:5], v[6:7]
	v_fmamk_f32 v111, v31, 0xba000000, v39
	v_fmamk_f32 v41, v31, 0xba000000, v41
	v_fmamk_f32 v116, v31, 0xba000000, v16
	v_mul_f32_e32 v16, v110, v110
	v_mul_f32_e32 v20, v40, v40
	v_pk_add_f32 v[4:5], v[32:33], v[10:11]
	v_pk_add_f32 v[0:1], v[0:1], v[2:3]
	v_fmamk_f32 v113, v31, 0xba000000, v37
	v_fmamk_f32 v112, v31, 0xba000000, v36
	v_fmamk_f32 v35, v31, 0xba000000, v35
	v_fmac_f32_e32 v34, 0xba000000, v31
	v_fmamk_f32 v115, v31, 0xba000000, v23
	v_fmamk_f32 v114, v31, 0xba000000, v22
	v_fmamk_f32 v25, v31, 0xba000000, v25
	v_fmac_f32_e32 v24, 0xba000000, v31
	v_fmamk_f32 v117, v31, 0xba000000, v17
	v_pk_fma_f32 v[8:9], v[110:111], v[110:111], v[16:17] op_sel_hi:[1,1,0]
	v_pk_fma_f32 v[16:17], v[40:41], v[40:41], v[20:21] op_sel_hi:[1,1,0]
	v_pk_add_f32 v[2:3], v[4:5], v[4:5] op_sel_hi:[0,1]
	v_pk_add_f32 v[0:1], v[0:1], v[0:1] op_sel_hi:[0,1]
	v_pk_mul_f32 v[22:23], v[24:25], v[24:25]
	v_pk_mul_f32 v[26:27], v[114:115], v[114:115]
	v_mul_f32_e32 v8, v34, v34
	v_mul_f32_e32 v16, v35, v35
	v_mul_f32_e32 v2, v112, v112
	v_mul_f32_e32 v0, v113, v113
	v_fmac_f32_e32 v18, 0xba000000, v31
	v_pk_mov_b32 v[20:21], v[26:27], v[22:23] op_sel:[1,0]
	v_mov_b32_e32 v27, v23
	v_pk_add_f32 v[4:5], v[8:9], v[16:17]
	v_pk_add_f32 v[0:1], v[2:3], v[0:1]
	v_fmamk_f32 v19, v31, 0xba000000, v19
	v_mul_f32_e32 v28, v116, v116
	v_mul_f32_e32 v30, v18, v18
	v_pk_add_f32 v[6:7], v[20:21], v[26:27]
	v_pk_add_f32 v[0:1], v[4:5], v[0:1]
	v_fmamk_f32 v119, v31, 0xba000000, v15
	v_pk_fma_f32 v[22:23], v[116:117], v[116:117], v[28:29] op_sel_hi:[1,1,0]
	v_pk_fma_f32 v[28:29], v[18:19], v[18:19], v[30:31] op_sel_hi:[1,1,0]
	v_pk_add_f32 v[6:7], v[6:7], v[6:7] op_sel_hi:[0,1]
	v_pk_add_f32 v[0:1], v[0:1], v[0:1] op_sel_hi:[0,1]
	v_fmamk_f32 v118, v31, 0xba000000, v14
	v_fmamk_f32 v13, v31, 0xba000000, v13
	v_fmac_f32_e32 v12, 0xba000000, v31
	v_mul_f32_e32 v22, v12, v12
	v_mul_f32_e32 v28, v13, v13
	v_mul_f32_e32 v6, v118, v118
	v_mul_f32_e32 v0, v119, v119
	v_pk_add_f32 v[2:3], v[22:23], v[28:29]
	v_pk_add_f32 v[0:1], v[6:7], v[0:1]
	v_add_u32_e32 v42, s64, v97
	v_pk_add_f32 v[0:1], v[2:3], v[0:1]
	v_cmp_gt_i32_e32 vcc, s0, v42
	v_add_f32_e32 v0, v0, v1
	ds_bpermute_b32 v1, v90, v0
	s_waitcnt lgkmcnt(0)
	v_add_f32_e32 v1, v0, v1
	ds_bpermute_b32 v2, v91, v1
	v_cndmask_b32_e32 v0, v97, v42, vcc
	s_waitcnt lgkmcnt(0)
	v_add_f32_e32 v4, v1, v2
	ds_bpermute_b32 v5, v92, v4
	v_ashrrev_i32_e32 v1, 31, v0
	v_lshlrev_b64 v[0:1], 13, v[0:1]
	v_lshl_add_u64 v[0:1], s[16:17], 0, v[0:1]
	v_lshl_add_u64 v[2:3], v[0:1], 0, v[54:55]
	s_waitcnt lgkmcnt(0)
	v_add_f32_e32 v4, v4, v5
	ds_bpermute_b32 v5, v93, v4
	global_load_dwordx4 v[36:39], v[2:3], off nt
	global_load_dwordx4 v[30:33], v[2:3], off offset:1024 nt
	global_load_dwordx4 v[26:29], v[2:3], off offset:2048 nt
	global_load_dwordx4 v[20:23], v[2:3], off offset:3072 nt
	v_lshl_add_u64 v[2:3], v[0:1], 0, v[82:83]
	v_lshl_add_u64 v[48:49], v[0:1], 0, v[86:87]
	v_lshl_add_u64 v[120:121], v[0:1], 0, v[88:89]
	s_waitcnt lgkmcnt(0)
	v_add_f32_e32 v6, v4, v5
	ds_bpermute_b32 v7, v94, v6
	v_lshl_add_u64 v[4:5], v[0:1], 0, v[84:85]
	global_load_dwordx4 v[14:17], v[2:3], off nt
	global_load_dwordx4 v[8:11], v[4:5], off nt
	s_waitcnt lgkmcnt(0)
	v_add_f32_e32 v6, v6, v7
	ds_bpermute_b32 v7, v95, v6
	s_waitcnt lgkmcnt(0)
	v_add_f32_e32 v2, v6, v7
	v_fmamk_f32 v2, v2, 0x3a000000, v96
	v_mul_f32_e32 v3, 0x4b800000, v2
	v_cmp_gt_f32_e64 s[8:9], s1, v2
	s_nop 1
	v_cndmask_b32_e64 v2, v2, v3, s[8:9]
	v_rsq_f32_e32 v43, v2
	global_load_dwordx4 v[4:7], v[48:49], off nt
	global_load_dwordx4 v[0:3], v[120:121], off nt
	v_mul_f32_e32 v48, 0x45800000, v43
	v_cndmask_b32_e64 v120, v43, v48, s[8:9]
	v_pk_mul_f32 v[48:49], v[50:51], v[120:121] op_sel_hi:[1,0]
	v_pk_mul_f32 v[50:51], v[52:53], v[120:121] op_sel_hi:[1,0]
	s_waitcnt vmcnt(8)
	v_pk_fma_f32 v[48:49], v[98:99], v[48:49], v[102:103]
	v_pk_fma_f32 v[50:51], v[100:101], v[50:51], v[104:105]
	v_cvt_pk_bf16_f32 v48, v48, v49
	v_cvt_pk_bf16_f32 v49, v50, v51
	global_store_dwordx2 v[78:79], v[48:49], off
	s_nop 1
	v_mov_b64_e32 v[48:49], v[140:141]
	v_mov_b64_e32 v[50:51], v[142:143]
	s_nop 0
	v_mov_b64_e32 v[98:99], v[144:145]
	v_mov_b64_e32 v[100:101], v[146:147]
	v_pk_mul_f32 v[46:47], v[46:47], v[120:121] op_sel_hi:[1,0]
	v_pk_mul_f32 v[52:53], v[106:107], v[120:121] op_sel_hi:[1,0]
	v_pk_mul_f32 v[44:45], v[44:45], v[120:121] op_sel_hi:[1,0]
	v_pk_mul_f32 v[40:41], v[40:41], v[120:121] op_sel_hi:[1,0]
	v_pk_mul_f32 v[34:35], v[34:35], v[120:121] op_sel_hi:[1,0]
	v_pk_mul_f32 v[24:25], v[24:25], v[120:121] op_sel_hi:[1,0]
	v_pk_mul_f32 v[18:19], v[18:19], v[120:121] op_sel_hi:[1,0]
	v_pk_mul_f32 v[12:13], v[12:13], v[120:121] op_sel_hi:[1,0]
	v_pk_fma_f32 v[50:51], v[50:51], v[52:53], v[100:101]
	v_pk_fma_f32 v[46:47], v[48:49], v[46:47], v[98:99]
	v_pk_mul_f32 v[98:99], v[108:109], v[120:121] op_sel_hi:[1,0]
	v_cvt_pk_bf16_f32 v46, v46, v47
	v_cvt_pk_bf16_f32 v47, v50, v51
	global_store_dwordx2 v[78:79], v[46:47], off offset:512
	s_nop 1
	v_mov_b64_e32 v[46:47], v[148:149]
	v_mov_b64_e32 v[48:49], v[150:151]
	s_nop 0
	v_mov_b64_e32 v[50:51], v[156:157]
	v_mov_b64_e32 v[52:53], v[158:159]
	v_pk_fma_f32 v[44:45], v[48:49], v[44:45], v[52:53]
	v_pk_fma_f32 v[46:47], v[46:47], v[98:99], v[50:51]
	v_pk_mul_f32 v[52:53], v[110:111], v[120:121] op_sel_hi:[1,0]
	v_cvt_pk_bf16_f32 v46, v46, v47
	v_cvt_pk_bf16_f32 v47, v44, v45
	global_store_dwordx2 v[78:79], v[46:47], off offset:1024
	s_nop 1
	v_mov_b64_e32 v[44:45], v[160:161]
	v_mov_b64_e32 v[46:47], v[162:163]
	s_nop 0
	v_mov_b64_e32 v[48:49], v[164:165]
	v_mov_b64_e32 v[50:51], v[166:167]
	v_pk_fma_f32 v[40:41], v[46:47], v[40:41], v[50:51]
	v_pk_fma_f32 v[44:45], v[44:45], v[52:53], v[48:49]
	s_nop 0
	v_cvt_pk_bf16_f32 v44, v44, v45
	v_cvt_pk_bf16_f32 v45, v40, v41
	global_store_dwordx2 v[78:79], v[44:45], off offset:1536
	s_nop 1
	v_mov_b64_e32 v[44:45], v[168:169]
	v_mov_b64_e32 v[46:47], v[170:171]
	s_nop 0
	v_mov_b64_e32 v[48:49], v[172:173]
	v_mov_b64_e32 v[50:51], v[174:175]
	v_pk_mul_f32 v[40:41], v[112:113], v[120:121] op_sel_hi:[1,0]
	v_pk_fma_f32 v[34:35], v[44:45], v[34:35], v[48:49]
	v_pk_fma_f32 v[40:41], v[46:47], v[40:41], v[50:51]
	v_cvt_pk_bf16_f32 v34, v34, v35
	v_cvt_pk_bf16_f32 v35, v40, v41
	global_store_dwordx2 v[78:79], v[34:35], off offset:2048
	s_nop 1
	v_mov_b64_e32 v[44:45], v[176:177]
	v_mov_b64_e32 v[46:47], v[178:179]
	v_mov_b64_e32 v[48:49], v[180:181]
	v_mov_b64_e32 v[50:51], v[182:183]
	v_pk_mul_f32 v[34:35], v[114:115], v[120:121] op_sel_hi:[1,0]
	v_pk_fma_f32 v[24:25], v[46:47], v[24:25], v[50:51]
	v_pk_fma_f32 v[34:35], v[44:45], v[34:35], v[48:49]
	s_nop 0
	v_cvt_pk_bf16_f32 v34, v34, v35
	v_cvt_pk_bf16_f32 v35, v24, v25
	global_store_dwordx2 v[78:79], v[34:35], off offset:2560
	s_nop 1
	v_mov_b64_e32 v[44:45], v[184:185]
	v_mov_b64_e32 v[46:47], v[186:187]
	v_mov_b64_e32 v[48:49], v[188:189]
	v_mov_b64_e32 v[50:51], v[190:191]
	v_pk_mul_f32 v[24:25], v[116:117], v[120:121] op_sel_hi:[1,0]
	v_pk_fma_f32 v[18:19], v[46:47], v[18:19], v[50:51]
	v_pk_fma_f32 v[24:25], v[44:45], v[24:25], v[48:49]
	s_nop 0
	v_cvt_pk_bf16_f32 v24, v24, v25
	v_cvt_pk_bf16_f32 v25, v18, v19
	global_store_dwordx2 v[78:79], v[24:25], off offset:3072
	s_nop 1
	v_mov_b64_e32 v[44:45], v[192:193]
	v_mov_b64_e32 v[46:47], v[194:195]
	v_mov_b64_e32 v[48:49], v[196:197]
	v_mov_b64_e32 v[50:51], v[198:199]
	v_pk_mul_f32 v[18:19], v[118:119], v[120:121] op_sel_hi:[1,0]
	v_pk_fma_f32 v[12:13], v[44:45], v[12:13], v[48:49]
	v_pk_fma_f32 v[18:19], v[46:47], v[18:19], v[50:51]
	v_cvt_pk_bf16_f32 v12, v12, v13
	v_cvt_pk_bf16_f32 v13, v18, v19
	global_store_dwordx2 v[78:79], v[12:13], off offset:3584
	s_and_saveexec_b64 s[8:9], vcc
	s_cbranch_execz .LBB0_1423
	s_waitcnt vmcnt(0)
	v_mov_b32_e32 v12, v36
	v_mov_b32_e32 v13, v30
	v_mov_b32_e32 v18, v37
	v_mov_b32_e32 v19, v31
	v_pk_add_f32 v[12:13], v[12:13], v[18:19]
	v_mov_b32_e32 v18, v38
	v_mov_b32_e32 v19, v32
	v_mov_b32_e32 v24, v39
	v_mov_b32_e32 v25, v33
	v_pk_add_f32 v[18:19], v[18:19], v[24:25]
	v_mov_b32_e32 v24, v26
	v_pk_add_f32 v[12:13], v[12:13], v[18:19]
	v_mov_b32_e32 v18, v27
	v_mov_b32_e32 v19, v28
	v_mov_b32_e32 v25, v29
	v_pk_add_f32 v[18:19], v[18:19], v[24:25]
	v_add_f32_e32 v12, 0, v12
	v_pk_add_f32 v[18:19], v[18:19], v[18:19] op_sel:[0,1] op_sel_hi:[1,0]
	v_add_f32_e32 v12, v12, v13
	v_add_f32_e32 v24, v20, v21
	v_add_f32_e32 v34, v22, v23
	v_mov_b32_e32 v13, v14
	v_mov_b32_e32 v19, v15
	v_mov_b32_e32 v25, v16
	v_mov_b32_e32 v35, v17
	v_pk_add_f32 v[12:13], v[12:13], v[18:19]
	v_pk_add_f32 v[18:19], v[24:25], v[34:35]
	v_mov_b32_e32 v24, v8
	v_pk_add_f32 v[12:13], v[12:13], v[18:19]
	v_mov_b32_e32 v18, v9
	v_mov_b32_e32 v19, v10
	v_mov_b32_e32 v25, v11
	v_pk_add_f32 v[18:19], v[18:19], v[24:25]
	v_pk_add_f32 v[12:13], v[12:13], v[12:13] op_sel:[0,1] op_sel_hi:[1,0]
	v_pk_add_f32 v[18:19], v[18:19], v[18:19] op_sel:[0,1] op_sel_hi:[1,0]
	v_add_f32_e32 v24, v4, v5
	v_add_f32_e32 v34, v6, v7
	v_mov_b32_e32 v13, v0
	v_mov_b32_e32 v19, v1
	v_mov_b32_e32 v25, v2
	v_mov_b32_e32 v35, v3
	v_pk_add_f32 v[12:13], v[12:13], v[18:19]
	v_pk_add_f32 v[18:19], v[24:25], v[34:35]
	s_nop 0
	v_pk_add_f32 v[12:13], v[12:13], v[18:19]
	s_nop 0
	v_add_f32_e32 v12, v12, v13
	ds_bpermute_b32 v13, v90, v12
	s_waitcnt lgkmcnt(0)
	v_add_f32_e32 v12, v12, v13
	ds_bpermute_b32 v13, v91, v12
	s_waitcnt lgkmcnt(0)
	v_add_f32_e32 v12, v12, v13
	ds_bpermute_b32 v13, v92, v12
	s_waitcnt lgkmcnt(0)
	v_add_f32_e32 v12, v12, v13
	ds_bpermute_b32 v13, v93, v12
	s_waitcnt lgkmcnt(0)
	v_add_f32_e32 v12, v12, v13
	ds_bpermute_b32 v13, v94, v12
	s_waitcnt lgkmcnt(0)
	v_add_f32_e32 v12, v12, v13
	ds_bpermute_b32 v13, v95, v12
	s_waitcnt lgkmcnt(0)
	v_add_f32_e32 v43, v12, v13
	v_fmamk_f32 v37, v43, 0xba000000, v37
	v_fmamk_f32 v31, v43, 0xba000000, v31
	v_fmamk_f32 v13, v43, 0xba000000, v39
	v_fmac_f32_e32 v36, 0xba000000, v43
	v_fmamk_f32 v33, v43, 0xba000000, v33
	v_fmac_f32_e32 v30, 0xba000000, v43
	v_mov_b32_e32 v24, v37
	v_mov_b32_e32 v25, v31
	v_fmamk_f32 v12, v43, 0xba000000, v38
	v_fmamk_f32 v32, v43, 0xba000000, v32
	v_mov_b32_e32 v18, v36
	v_mov_b32_e32 v19, v30
	v_pk_mul_f32 v[24:25], v[24:25], v[24:25]
	v_mov_b32_e32 v34, v13
	v_mov_b32_e32 v35, v33
	v_pk_fma_f32 v[18:19], v[18:19], v[18:19], v[24:25]
	v_mov_b32_e32 v24, v12
	v_mov_b32_e32 v25, v32
	v_pk_mul_f32 v[34:35], v[34:35], v[34:35]
	v_fmamk_f32 v29, v43, 0xba000000, v29
	v_pk_fma_f32 v[24:25], v[24:25], v[24:25], v[34:35]
	v_fmamk_f32 v35, v43, 0xba000000, v27
	v_pk_add_f32 v[18:19], v[18:19], v[24:25]
	v_fmamk_f32 v34, v43, 0xba000000, v26
	v_fmac_f32_e32 v28, 0xba000000, v43
	v_pk_add_f32 v[18:19], v[18:19], v[18:19] op_sel_hi:[0,1]
	v_pk_mul_f32 v[24:25], v[28:29], v[28:29]
	v_pk_mul_f32 v[26:27], v[34:35], v[34:35]
	v_fmamk_f32 v20, v43, 0xba000000, v20
	v_pk_mov_b32 v[38:39], v[26:27], v[24:25] op_sel:[1,0]
	v_mov_b32_e32 v27, v25
	v_fmamk_f32 v21, v43, 0xba000000, v21
	v_fmac_f32_e32 v22, 0xba000000, v43
	v_mul_f32_e32 v18, v20, v20
	v_pk_add_f32 v[24:25], v[38:39], v[26:27]
	v_fmamk_f32 v23, v43, 0xba000000, v23
	v_pk_fma_f32 v[26:27], v[20:21], v[20:21], v[18:19] op_sel_hi:[1,1,0]
	v_mul_f32_e32 v18, v22, v22
	v_pk_add_f32 v[24:25], v[24:25], v[24:25] op_sel_hi:[0,1]
	v_pk_fma_f32 v[38:39], v[22:23], v[22:23], v[18:19] op_sel_hi:[1,1,0]
	v_fmamk_f32 v41, v43, 0xba000000, v17
	v_fmamk_f32 v40, v43, 0xba000000, v16
	v_fmamk_f32 v15, v43, 0xba000000, v15
	v_fmac_f32_e32 v14, 0xba000000, v43
	v_mul_f32_e32 v26, v14, v14
	v_mul_f32_e32 v38, v15, v15
	v_mul_f32_e32 v24, v40, v40
	v_mul_f32_e32 v18, v41, v41
	v_pk_add_f32 v[16:17], v[26:27], v[38:39]
	v_pk_add_f32 v[18:19], v[24:25], v[18:19]
	v_fmamk_f32 v9, v43, 0xba000000, v9
	v_pk_add_f32 v[16:17], v[16:17], v[18:19]
	v_fmamk_f32 v8, v43, 0xba000000, v8
	v_pk_add_f32 v[38:39], v[16:17], v[16:17] op_sel_hi:[0,1]
	v_mov_b64_e32 v[16:17], v[132:133]
	v_mov_b64_e32 v[18:19], v[134:135]
	v_mov_b64_e32 v[24:25], v[136:137]
	v_mov_b64_e32 v[26:27], v[138:139]
	v_fmamk_f32 v11, v43, 0xba000000, v11
	v_fmac_f32_e32 v10, 0xba000000, v43
	v_pk_mul_f32 v[44:45], v[10:11], v[10:11]
	v_pk_mul_f32 v[46:47], v[8:9], v[8:9]
	v_fmac_f32_e32 v6, 0xba000000, v43
	v_pk_mov_b32 v[48:49], v[46:47], v[44:45] op_sel:[1,0]
	v_mov_b32_e32 v47, v45
	v_pk_add_f32 v[44:45], v[48:49], v[46:47]
	v_fmamk_f32 v46, v43, 0xba000000, v4
	v_fmamk_f32 v47, v43, 0xba000000, v5
	v_mul_f32_e32 v4, v46, v46
	v_pk_fma_f32 v[4:5], v[46:47], v[46:47], v[4:5] op_sel_hi:[1,1,0]
	v_fmamk_f32 v7, v43, 0xba000000, v7
	v_mul_f32_e32 v4, v6, v6
	v_pk_add_f32 v[44:45], v[44:45], v[44:45] op_sel_hi:[0,1]
	v_pk_fma_f32 v[48:49], v[6:7], v[6:7], v[4:5] op_sel_hi:[1,1,0]
	v_fmamk_f32 v51, v43, 0xba000000, v3
	v_fmamk_f32 v50, v43, 0xba000000, v2
	v_fmamk_f32 v1, v43, 0xba000000, v1
	v_fmac_f32_e32 v0, 0xba000000, v43
	v_mul_f32_e32 v4, v0, v0
	v_mul_f32_e32 v48, v1, v1
	v_mul_f32_e32 v44, v50, v50
	v_mul_f32_e32 v38, v51, v51
	v_pk_add_f32 v[2:3], v[4:5], v[48:49]
	v_pk_add_f32 v[4:5], v[44:45], v[38:39]
	v_ashrrev_i32_e32 v43, 31, v42
	v_pk_add_f32 v[2:3], v[2:3], v[4:5]
	s_nop 0
	v_add_f32_e32 v2, v2, v3
	ds_bpermute_b32 v3, v90, v2
	s_waitcnt lgkmcnt(0)
	v_add_f32_e32 v2, v2, v3
	ds_bpermute_b32 v3, v91, v2
	s_waitcnt lgkmcnt(0)
	v_add_f32_e32 v2, v2, v3
	ds_bpermute_b32 v3, v92, v2
	s_waitcnt lgkmcnt(0)
	v_add_f32_e32 v2, v2, v3
	ds_bpermute_b32 v3, v93, v2
	s_waitcnt lgkmcnt(0)
	v_add_f32_e32 v2, v2, v3
	ds_bpermute_b32 v3, v94, v2
	s_waitcnt lgkmcnt(0)
	v_add_f32_e32 v2, v2, v3
	ds_bpermute_b32 v3, v95, v2
	s_waitcnt lgkmcnt(0)
	v_add_f32_e32 v2, v2, v3
	v_fmamk_f32 v2, v2, 0x3a000000, v96
	v_mul_f32_e32 v3, 0x4b800000, v2
	v_cmp_gt_f32_e32 vcc, s1, v2
	s_nop 1
	v_cndmask_b32_e32 v2, v2, v3, vcc
	v_rsq_f32_e32 v2, v2
	s_nop 0
	v_mul_f32_e32 v3, 0x45800000, v2
	v_cndmask_b32_e32 v38, v2, v3, vcc
	v_pk_mul_f32 v[4:5], v[36:37], v[38:39] op_sel_hi:[1,0]
	v_pk_mul_f32 v[12:13], v[12:13], v[38:39] op_sel_hi:[1,0]
	v_lshlrev_b64 v[2:3], 12, v[42:43]
	v_pk_fma_f32 v[12:13], v[18:19], v[12:13], v[26:27]
	v_pk_fma_f32 v[4:5], v[16:17], v[4:5], v[24:25]
	v_lshl_add_u64 v[24:25], v[76:77], 0, v[2:3]
	v_cvt_pk_bf16_f32 v4, v4, v5
	v_cvt_pk_bf16_f32 v5, v12, v13
	global_store_dwordx2 v[24:25], v[4:5], off
	s_nop 1
	v_mov_b64_e32 v[2:3], v[140:141]
	v_mov_b64_e32 v[4:5], v[142:143]
	s_nop 0
	v_mov_b64_e32 v[16:17], v[144:145]
	v_mov_b64_e32 v[18:19], v[146:147]
	v_pk_mul_f32 v[12:13], v[30:31], v[38:39] op_sel_hi:[1,0]
	v_pk_mul_f32 v[26:27], v[32:33], v[38:39] op_sel_hi:[1,0]
	v_pk_mul_f32 v[8:9], v[8:9], v[38:39] op_sel_hi:[1,0]
	v_pk_mul_f32 v[10:11], v[10:11], v[38:39] op_sel_hi:[1,0]
	v_pk_mul_f32 v[6:7], v[6:7], v[38:39] op_sel_hi:[1,0]
	v_pk_mul_f32 v[0:1], v[0:1], v[38:39] op_sel_hi:[1,0]
	v_pk_fma_f32 v[4:5], v[4:5], v[26:27], v[18:19]
	v_pk_fma_f32 v[2:3], v[2:3], v[12:13], v[16:17]
	v_pk_mul_f32 v[12:13], v[34:35], v[38:39] op_sel_hi:[1,0]
	v_cvt_pk_bf16_f32 v2, v2, v3
	v_cvt_pk_bf16_f32 v3, v4, v5
	global_store_dwordx2 v[24:25], v[2:3], off offset:512
	s_nop 1
	v_mov_b64_e32 v[2:3], v[148:149]
	v_mov_b64_e32 v[4:5], v[150:151]
	s_nop 0
	v_mov_b64_e32 v[16:17], v[156:157]
	v_mov_b64_e32 v[18:19], v[158:159]
	v_pk_mul_f32 v[26:27], v[28:29], v[38:39] op_sel_hi:[1,0]
	v_pk_fma_f32 v[2:3], v[2:3], v[12:13], v[16:17]
	v_pk_fma_f32 v[4:5], v[4:5], v[26:27], v[18:19]
	v_cvt_pk_bf16_f32 v2, v2, v3
	v_cvt_pk_bf16_f32 v3, v4, v5
	global_store_dwordx2 v[24:25], v[2:3], off offset:1024
	s_nop 1
	v_mov_b64_e32 v[2:3], v[160:161]
	v_mov_b64_e32 v[4:5], v[162:163]
	s_nop 0
	v_mov_b64_e32 v[16:17], v[164:165]
	v_mov_b64_e32 v[18:19], v[166:167]
	v_pk_mul_f32 v[12:13], v[20:21], v[38:39] op_sel_hi:[1,0]
	v_pk_mul_f32 v[20:21], v[22:23], v[38:39] op_sel_hi:[1,0]
	v_pk_fma_f32 v[2:3], v[2:3], v[12:13], v[16:17]
	v_pk_fma_f32 v[4:5], v[4:5], v[20:21], v[18:19]
	v_cvt_pk_bf16_f32 v2, v2, v3
	v_cvt_pk_bf16_f32 v3, v4, v5
	global_store_dwordx2 v[24:25], v[2:3], off offset:1536
	s_nop 1
	v_mov_b64_e32 v[2:3], v[168:169]
	v_mov_b64_e32 v[4:5], v[170:171]
	s_nop 0
	v_mov_b64_e32 v[16:17], v[172:173]
	v_mov_b64_e32 v[18:19], v[174:175]
	v_pk_mul_f32 v[12:13], v[14:15], v[38:39] op_sel_hi:[1,0]
	v_pk_mul_f32 v[14:15], v[40:41], v[38:39] op_sel_hi:[1,0]
	v_pk_fma_f32 v[2:3], v[2:3], v[12:13], v[16:17]
	v_pk_fma_f32 v[4:5], v[4:5], v[14:15], v[18:19]
	v_cvt_pk_bf16_f32 v2, v2, v3
	v_cvt_pk_bf16_f32 v3, v4, v5
	global_store_dwordx2 v[24:25], v[2:3], off offset:2048
	s_nop 1
	v_mov_b64_e32 v[2:3], v[176:177]
	v_mov_b64_e32 v[4:5], v[178:179]
	s_nop 0
	v_mov_b64_e32 v[12:13], v[180:181]
	v_mov_b64_e32 v[14:15], v[182:183]
	v_pk_fma_f32 v[4:5], v[4:5], v[10:11], v[14:15]
	v_pk_fma_f32 v[2:3], v[2:3], v[8:9], v[12:13]
	v_pk_mul_f32 v[12:13], v[46:47], v[38:39] op_sel_hi:[1,0]
	v_cvt_pk_bf16_f32 v2, v2, v3
	v_cvt_pk_bf16_f32 v3, v4, v5
	global_store_dwordx2 v[24:25], v[2:3], off offset:2560
	s_nop 1
	v_mov_b64_e32 v[2:3], v[184:185]
	v_mov_b64_e32 v[4:5], v[186:187]
	s_nop 0
	v_mov_b64_e32 v[8:9], v[188:189]
	v_mov_b64_e32 v[10:11], v[190:191]
	v_pk_fma_f32 v[4:5], v[4:5], v[6:7], v[10:11]
	v_pk_fma_f32 v[2:3], v[2:3], v[12:13], v[8:9]
	v_pk_mul_f32 v[10:11], v[50:51], v[38:39] op_sel_hi:[1,0]
	v_cvt_pk_bf16_f32 v2, v2, v3
	v_cvt_pk_bf16_f32 v3, v4, v5
	global_store_dwordx2 v[24:25], v[2:3], off offset:3072
	s_nop 1
	v_mov_b64_e32 v[2:3], v[192:193]
	v_mov_b64_e32 v[4:5], v[194:195]
	s_nop 0
	v_mov_b64_e32 v[6:7], v[196:197]
	v_mov_b64_e32 v[8:9], v[198:199]
	v_pk_fma_f32 v[4:5], v[4:5], v[10:11], v[8:9]
	v_pk_fma_f32 v[0:1], v[2:3], v[0:1], v[6:7]
	s_nop 0
	v_cvt_pk_bf16_f32 v0, v0, v1
	v_cvt_pk_bf16_f32 v1, v4, v5
	global_store_dwordx2 v[24:25], v[0:1], off offset:3584
	s_branch .LBB0_1423

.LBB0_1622:
	s_or_b64 exec, exec, s[2:3]
	s_waitcnt lgkmcnt(0)
	s_barrier
	s_and_saveexec_b64 s[0:1], s[4:5]
	s_cbranch_execz .LBB0_1627
	v_mbcnt_hi_u32_b32 v1, -1, v152
	v_and_b32_e32 v3, 64, v1
	v_xor_b32_e32 v2, 1, v1
	v_add_u32_e32 v3, 64, v3
	v_cmp_lt_i32_e32 vcc, v2, v3
	v_readlane_b32 s0, v254, 3
	v_readlane_b32 s1, v254, 4
	v_cndmask_b32_e32 v2, v1, v2, vcc
	v_lshlrev_b32_e32 v80, 2, v2
	v_xor_b32_e32 v2, 2, v1
	v_cmp_lt_i32_e32 vcc, v2, v3
	s_load_dwordx4 s[4:7], s[0:1], 0xb0
	s_load_dwordx2 s[2:3], s[0:1], 0xc0
	v_cndmask_b32_e32 v2, v1, v2, vcc
	v_lshlrev_b32_e32 v81, 2, v2
	v_xor_b32_e32 v2, 4, v1
	v_cmp_lt_i32_e32 vcc, v2, v3
	v_and_b32_e32 v0, 0xfc, v212
	v_mov_b32_e32 v39, 0
	v_cndmask_b32_e32 v2, v1, v2, vcc
	v_lshlrev_b32_e32 v82, 2, v2
	v_xor_b32_e32 v2, 8, v1
	v_cmp_lt_i32_e32 vcc, v2, v3
	v_lshlrev_b32_e32 v38, 2, v0
	s_waitcnt lgkmcnt(0)
	v_lshl_add_u64 v[40:41], s[4:5], 0, v[38:39]
	v_cndmask_b32_e32 v2, v1, v2, vcc
	v_lshlrev_b32_e32 v83, 2, v2
	v_xor_b32_e32 v2, 16, v1
	v_cmp_lt_i32_e32 vcc, v2, v3
	v_lshl_add_u64 v[42:43], s[6:7], 0, v[38:39]
	v_or_b32_e32 v4, 0x500, v0
	v_cndmask_b32_e32 v2, v1, v2, vcc
	v_lshlrev_b32_e32 v84, 2, v2
	v_xor_b32_e32 v2, 32, v1
	v_cmp_lt_i32_e32 vcc, v2, v3
	v_or_b32_e32 v6, 0x600, v0
	v_or_b32_e32 v8, 0x700, v0
	v_cndmask_b32_e32 v1, v1, v2, vcc
	v_or_b32_e32 v2, 0x400, v0
	v_lshlrev_b32_e32 v38, 2, v2
	v_lshl_add_u64 v[44:45], s[4:5], 0, v[38:39]
	v_lshl_add_u64 v[46:47], s[6:7], 0, v[38:39]
	v_lshlrev_b32_e32 v38, 2, v4
	v_lshl_add_u64 v[48:49], s[4:5], 0, v[38:39]
	v_lshl_add_u64 v[50:51], s[6:7], 0, v[38:39]
	v_lshlrev_b32_e32 v38, 2, v6
	v_lshl_add_u64 v[52:53], s[4:5], 0, v[38:39]
	v_lshl_add_u64 v[54:55], s[6:7], 0, v[38:39]
	v_lshlrev_b32_e32 v38, 2, v8
	v_lshlrev_b32_e32 v85, 2, v1
	v_lshl_add_u64 v[56:57], s[4:5], 0, v[38:39]
	v_lshl_add_u64 v[58:59], s[6:7], 0, v[38:39]
	s_mov_b64 s[4:5], 0
	s_movk_i32 s6, 0x4000
	v_lshlrev_b32_e32 v38, 2, v0
	v_lshlrev_b32_e32 v60, 2, v2
	v_lshlrev_b32_e32 v62, 2, v4
	v_lshlrev_b32_e32 v64, 2, v6
	v_lshlrev_b32_e32 v66, 2, v8
	v_mov_b32_e32 v86, 0x3727c5ac
	s_mov_b32 s7, 0x800000
	s_movk_i32 s8, 0x3fff
	v_mov_b32_e32 v61, v39
	v_mov_b32_e32 v63, v39
	v_mov_b32_e32 v65, v39
	v_mov_b32_e32 v67, v39
	global_load_dwordx4 v[132:135], v[40:41], off
	global_load_dwordx4 v[136:139], v[42:43], off
	global_load_dwordx4 v[140:143], v[40:41], off offset:1024
	global_load_dwordx4 v[144:147], v[42:43], off offset:1024
	global_load_dwordx4 v[148:151], v[40:41], off offset:2048
	global_load_dwordx4 v[156:159], v[42:43], off offset:2048
	global_load_dwordx4 v[160:163], v[40:41], off offset:3072
	global_load_dwordx4 v[164:167], v[42:43], off offset:3072
	global_load_dwordx4 v[168:171], v[44:45], off
	global_load_dwordx4 v[172:175], v[46:47], off
	global_load_dwordx4 v[176:179], v[48:49], off
	global_load_dwordx4 v[180:183], v[50:51], off
	global_load_dwordx4 v[184:187], v[52:53], off
	global_load_dwordx4 v[188:191], v[54:55], off
	global_load_dwordx4 v[192:195], v[56:57], off
	global_load_dwordx4 v[196:199], v[58:59], off
	s_waitcnt vmcnt(0)
	s_branch .LBB0_1625

.LBB0_1625:
	v_ashrrev_i32_e32 v129, 31, v128
	v_lshlrev_b64 v[0:1], 13, v[128:129]
	v_lshl_add_u64 v[0:1], s[2:3], 0, v[0:1]
	v_lshl_add_u64 v[74:75], v[0:1], 0, v[38:39]
	global_load_dwordx4 v[20:23], v[74:75], off offset:1024 nt
	global_load_dwordx4 v[28:31], v[74:75], off nt
	global_load_dwordx4 v[24:27], v[74:75], off offset:2048 nt
	global_load_dwordx4 v[16:19], v[74:75], off offset:3072 nt
	v_lshl_add_u64 v[36:37], v[0:1], 0, v[60:61]
	global_load_dwordx4 v[12:15], v[36:37], off nt
	v_lshl_add_u64 v[34:35], v[0:1], 0, v[62:63]
	global_load_dwordx4 v[8:11], v[34:35], off nt
	v_lshl_add_u64 v[70:71], v[0:1], 0, v[64:65]
	v_lshl_add_u64 v[68:69], v[0:1], 0, v[66:67]
	global_load_dwordx4 v[4:7], v[70:71], off nt
	global_load_dwordx4 v[0:3], v[68:69], off nt
	s_waitcnt vmcnt(7)
	v_mov_b32_e32 v32, v20
	s_waitcnt vmcnt(6)
	v_mov_b32_e32 v33, v28
	v_mov_b32_e32 v72, v21
	v_mov_b32_e32 v73, v29
	v_mov_b32_e32 v76, v22
	v_mov_b32_e32 v77, v30
	v_mov_b32_e32 v78, v23
	v_mov_b32_e32 v79, v31
	s_waitcnt vmcnt(5)
	v_mov_b32_e32 v88, v25
	v_mov_b32_e32 v89, v26
	v_mov_b32_e32 v90, v24
	v_mov_b32_e32 v91, v27
	v_pk_add_f32 v[32:33], v[32:33], v[72:73]
	v_pk_add_f32 v[72:73], v[76:77], v[78:79]
	v_pk_add_f32 v[76:77], v[88:89], v[90:91]
	v_pk_add_f32 v[32:33], v[32:33], v[72:73]
	v_pk_add_f32 v[72:73], v[76:77], v[76:77] op_sel_hi:[0,1]
	v_add_f32_e32 v33, 0, v33
	s_waitcnt vmcnt(4)
	v_add_f32_e32 v93, v16, v17
	v_add_f32_e32 v95, v18, v19
	s_waitcnt vmcnt(3)
	v_mov_b32_e32 v92, v12
	v_mov_b32_e32 v94, v13
	v_mov_b32_e32 v96, v15
	v_mov_b32_e32 v72, v14
	v_add_f32_e32 v97, v32, v33
	s_waitcnt vmcnt(2)
	v_mov_b32_e32 v98, v9
	v_mov_b32_e32 v99, v10
	v_mov_b32_e32 v100, v8
	v_mov_b32_e32 v101, v11
	v_pk_add_f32 v[78:79], v[92:93], v[94:95]
	v_pk_add_f32 v[32:33], v[72:73], v[96:97]
	v_pk_add_f32 v[88:89], v[98:99], v[100:101]
	v_pk_add_f32 v[32:33], v[78:79], v[32:33]
	v_pk_add_f32 v[76:77], v[88:89], v[88:89] op_sel_hi:[0,1]
	v_pk_add_f32 v[32:33], v[32:33], v[32:33] op_sel_hi:[0,1]
	s_waitcnt vmcnt(1)
	v_add_f32_e32 v103, v4, v5
	v_add_f32_e32 v105, v6, v7
	s_waitcnt vmcnt(0)
	v_mov_b32_e32 v102, v0
	v_mov_b32_e32 v104, v1
	v_mov_b32_e32 v76, v2
	v_mov_b32_e32 v32, v3
	v_pk_add_f32 v[90:91], v[102:103], v[104:105]
	v_pk_add_f32 v[32:33], v[76:77], v[32:33]
	s_nop 0
	v_pk_add_f32 v[32:33], v[90:91], v[32:33]
	s_nop 1
	v_mov_b64_e32 v[76:77], v[132:133]
	v_mov_b64_e32 v[78:79], v[134:135]
	s_nop 1
	v_mov_b64_e32 v[88:89], v[136:137]
	v_mov_b64_e32 v[90:91], v[138:139]
	v_add_f32_e32 v32, v32, v33
	ds_bpermute_b32 v33, v80, v32
	s_waitcnt lgkmcnt(0)
	v_add_f32_e32 v32, v32, v33
	ds_bpermute_b32 v33, v81, v32
	s_waitcnt lgkmcnt(0)
	v_add_f32_e32 v32, v32, v33
	ds_bpermute_b32 v33, v82, v32
	s_waitcnt lgkmcnt(0)
	v_add_f32_e32 v32, v32, v33
	ds_bpermute_b32 v33, v83, v32
	s_waitcnt lgkmcnt(0)
	v_add_f32_e32 v32, v32, v33
	ds_bpermute_b32 v33, v84, v32
	s_waitcnt lgkmcnt(0)
	v_add_f32_e32 v32, v32, v33
	ds_bpermute_b32 v33, v85, v32
	s_waitcnt lgkmcnt(0)
	v_add_f32_e32 v87, v32, v33
	v_fmamk_f32 v31, v87, 0xba000000, v31
	v_fmamk_f32 v29, v87, 0xba000000, v29
	v_fmamk_f32 v33, v87, 0xba000000, v23
	v_fmamk_f32 v21, v87, 0xba000000, v21
	v_fmamk_f32 v30, v87, 0xba000000, v30
	v_fmac_f32_e32 v28, 0xba000000, v87
	v_fmamk_f32 v32, v87, 0xba000000, v22
	v_fmac_f32_e32 v20, 0xba000000, v87
	v_fmamk_f32 v93, v87, 0xba000000, v25
	v_fmamk_f32 v92, v87, 0xba000000, v24
	v_fmamk_f32 v27, v87, 0xba000000, v27
	v_fmac_f32_e32 v26, 0xba000000, v87
	v_fmamk_f32 v97, v87, 0xba000000, v15
	v_fmamk_f32 v96, v87, 0xba000000, v14
	v_mov_b32_e32 v14, v29
	v_mov_b32_e32 v15, v21
	v_mov_b32_e32 v22, v31
	v_mov_b32_e32 v23, v33
	v_fmamk_f32 v95, v87, 0xba000000, v17
	v_fmamk_f32 v94, v87, 0xba000000, v16
	v_fmamk_f32 v99, v87, 0xba000000, v5
	v_fmamk_f32 v98, v87, 0xba000000, v4
	v_mov_b32_e32 v4, v28
	v_mov_b32_e32 v5, v20
	v_mov_b32_e32 v16, v30
	v_mov_b32_e32 v17, v32
	v_pk_mul_f32 v[24:25], v[26:27], v[26:27]
	v_pk_mul_f32 v[72:73], v[92:93], v[92:93]
	v_pk_mul_f32 v[14:15], v[14:15], v[14:15]
	v_pk_mul_f32 v[22:23], v[22:23], v[22:23]
	v_fmac_f32_e32 v18, 0xba000000, v87
	v_pk_mov_b32 v[110:111], v[72:73], v[24:25] op_sel:[1,0]
	v_mov_b32_e32 v73, v25
	v_pk_fma_f32 v[4:5], v[4:5], v[4:5], v[14:15]
	v_pk_fma_f32 v[14:15], v[16:17], v[16:17], v[22:23]
	v_fmamk_f32 v19, v87, 0xba000000, v19
	v_mul_f32_e32 v100, v94, v94
	v_mul_f32_e32 v102, v18, v18
	v_pk_add_f32 v[16:17], v[110:111], v[72:73]
	v_pk_add_f32 v[4:5], v[4:5], v[14:15]
	v_fmamk_f32 v13, v87, 0xba000000, v13
	v_fmac_f32_e32 v12, 0xba000000, v87
	v_pk_fma_f32 v[24:25], v[94:95], v[94:95], v[100:101] op_sel_hi:[1,1,0]
	v_pk_fma_f32 v[100:101], v[18:19], v[18:19], v[102:103] op_sel_hi:[1,1,0]
	v_pk_add_f32 v[14:15], v[16:17], v[16:17] op_sel_hi:[0,1]
	v_pk_add_f32 v[4:5], v[4:5], v[4:5] op_sel_hi:[0,1]
	v_mul_f32_e32 v24, v12, v12
	v_mul_f32_e32 v100, v13, v13
	v_mul_f32_e32 v14, v96, v96
	v_mul_f32_e32 v4, v97, v97
	v_fmamk_f32 v9, v87, 0xba000000, v9
	v_fmamk_f32 v8, v87, 0xba000000, v8
	v_fmamk_f32 v11, v87, 0xba000000, v11
	v_fmac_f32_e32 v10, 0xba000000, v87
	v_pk_add_f32 v[16:17], v[24:25], v[100:101]
	v_pk_add_f32 v[4:5], v[14:15], v[4:5]
	v_pk_mul_f32 v[104:105], v[10:11], v[10:11]
	v_pk_mul_f32 v[106:107], v[8:9], v[8:9]
	v_pk_add_f32 v[4:5], v[16:17], v[4:5]
	v_fmac_f32_e32 v6, 0xba000000, v87
	v_pk_mov_b32 v[102:103], v[106:107], v[104:105] op_sel:[1,0]
	v_mov_b32_e32 v107, v105
	v_pk_add_f32 v[4:5], v[4:5], v[4:5] op_sel_hi:[0,1]
	v_fmamk_f32 v7, v87, 0xba000000, v7
	v_mul_f32_e32 v108, v98, v98
	v_pk_add_f32 v[22:23], v[102:103], v[106:107]
	v_mul_f32_e32 v4, v6, v6
	v_pk_add_f32 v[22:23], v[22:23], v[22:23] op_sel_hi:[0,1]
	v_pk_fma_f32 v[14:15], v[98:99], v[98:99], v[108:109] op_sel_hi:[1,1,0]
	v_pk_fma_f32 v[16:17], v[6:7], v[6:7], v[4:5] op_sel_hi:[1,1,0]
	v_fmamk_f32 v101, v87, 0xba000000, v3
	v_fmamk_f32 v100, v87, 0xba000000, v2
	v_fmamk_f32 v1, v87, 0xba000000, v1
	v_fmac_f32_e32 v0, 0xba000000, v87
	v_mul_f32_e32 v14, v0, v0
	v_mul_f32_e32 v16, v1, v1
	v_mul_f32_e32 v22, v100, v100
	v_mul_f32_e32 v4, v101, v101
	v_pk_add_f32 v[2:3], v[14:15], v[16:17]
	v_pk_add_f32 v[4:5], v[22:23], v[4:5]
	v_add_u32_e32 v87, s64, v128
	v_pk_add_f32 v[2:3], v[2:3], v[4:5]
	v_cmp_gt_i32_e32 vcc, s6, v87
	v_add_f32_e32 v2, v2, v3
	ds_bpermute_b32 v3, v80, v2
	s_waitcnt lgkmcnt(0)
	v_add_f32_e32 v2, v2, v3
	ds_bpermute_b32 v3, v81, v2
	s_waitcnt lgkmcnt(0)
	v_add_f32_e32 v2, v2, v3
	ds_bpermute_b32 v3, v82, v2
	s_waitcnt lgkmcnt(0)
	v_add_f32_e32 v2, v2, v3
	ds_bpermute_b32 v3, v83, v2
	s_waitcnt lgkmcnt(0)
	v_add_f32_e32 v2, v2, v3
	ds_bpermute_b32 v3, v84, v2
	s_waitcnt lgkmcnt(0)
	v_add_f32_e32 v4, v2, v3
	ds_bpermute_b32 v5, v85, v4
	v_cndmask_b32_e32 v2, v128, v87, vcc
	v_ashrrev_i32_e32 v3, 31, v2
	v_lshlrev_b64 v[2:3], 13, v[2:3]
	v_lshl_add_u64 v[102:103], s[2:3], 0, v[2:3]
	s_waitcnt lgkmcnt(0)
	v_add_f32_e32 v2, v4, v5
	v_fmamk_f32 v2, v2, 0x3a000000, v86
	v_mul_f32_e32 v3, 0x4b800000, v2
	v_cmp_gt_f32_e64 s[0:1], s7, v2
	v_lshl_add_u64 v[72:73], v[102:103], 0, v[38:39]
	s_nop 0
	v_cndmask_b32_e64 v2, v2, v3, s[0:1]
	v_rsq_f32_e32 v14, v2
	global_load_dwordx4 v[22:25], v[72:73], off nt
	global_load_dwordx4 v[2:5], v[72:73], off offset:1024 nt
	v_mul_f32_e32 v15, 0x45800000, v14
	v_cndmask_b32_e64 v104, v14, v15, s[0:1]
	v_pk_mul_f32 v[14:15], v[28:29], v[104:105] op_sel_hi:[1,0]
	v_pk_mul_f32 v[16:17], v[30:31], v[104:105] op_sel_hi:[1,0]
	v_pk_fma_f32 v[14:15], v[76:77], v[14:15], v[88:89]
	v_pk_fma_f32 v[16:17], v[78:79], v[16:17], v[90:91]
	global_store_dwordx4 v[74:75], v[14:17], off nt
	s_nop 1
	v_mov_b64_e32 v[14:15], v[140:141]
	v_mov_b64_e32 v[16:17], v[142:143]
	s_nop 0
	s_nop 1
	v_mov_b64_e32 v[28:29], v[144:145]
	v_mov_b64_e32 v[30:31], v[146:147]
	v_pk_mul_f32 v[32:33], v[32:33], v[104:105] op_sel_hi:[1,0]
	v_pk_mul_f32 v[20:21], v[20:21], v[104:105] op_sel_hi:[1,0]
	v_pk_mul_f32 v[12:13], v[12:13], v[104:105] op_sel_hi:[1,0]
	v_pk_mul_f32 v[10:11], v[10:11], v[104:105] op_sel_hi:[1,0]
	v_pk_mul_f32 v[8:9], v[8:9], v[104:105] op_sel_hi:[1,0]
	v_pk_mul_f32 v[6:7], v[6:7], v[104:105] op_sel_hi:[1,0]
	v_pk_mul_f32 v[0:1], v[0:1], v[104:105] op_sel_hi:[1,0]
	v_pk_fma_f32 v[14:15], v[14:15], v[20:21], v[28:29]
	v_pk_fma_f32 v[16:17], v[16:17], v[32:33], v[30:31]
	global_store_dwordx4 v[74:75], v[14:17], off offset:1024 nt
	s_nop 1
	v_mov_b64_e32 v[76:77], v[148:149]
	v_mov_b64_e32 v[78:79], v[150:151]
	s_nop 1
	v_mov_b64_e32 v[88:89], v[156:157]
	v_mov_b64_e32 v[90:91], v[158:159]
	global_load_dwordx4 v[30:33], v[72:73], off offset:2048 nt
	s_nop 0
	global_load_dwordx4 v[14:17], v[72:73], off offset:3072 nt
	v_pk_mul_f32 v[20:21], v[26:27], v[104:105] op_sel_hi:[1,0]
	v_pk_mul_f32 v[26:27], v[92:93], v[104:105] op_sel_hi:[1,0]
	v_pk_fma_f32 v[28:29], v[78:79], v[20:21], v[90:91]
	v_pk_fma_f32 v[26:27], v[76:77], v[26:27], v[88:89]
	global_store_dwordx4 v[74:75], v[26:29], off offset:2048 nt
	s_nop 1
	v_mov_b64_e32 v[26:27], v[160:161]
	v_mov_b64_e32 v[28:29], v[162:163]
	s_nop 0
	s_nop 1
	v_mov_b64_e32 v[76:77], v[164:165]
	v_mov_b64_e32 v[78:79], v[166:167]
	v_pk_mul_f32 v[20:21], v[18:19], v[104:105] op_sel_hi:[1,0]
	v_pk_mul_f32 v[18:19], v[94:95], v[104:105] op_sel_hi:[1,0]
	v_pk_fma_f32 v[20:21], v[28:29], v[20:21], v[78:79]
	v_pk_fma_f32 v[18:19], v[26:27], v[18:19], v[76:77]
	global_store_dwordx4 v[74:75], v[18:21], off offset:3072 nt
	s_nop 1
	v_mov_b64_e32 v[88:89], v[168:169]
	v_mov_b64_e32 v[90:91], v[170:171]
	s_nop 1
	v_mov_b64_e32 v[92:93], v[172:173]
	v_mov_b64_e32 v[94:95], v[174:175]
	v_pk_mul_f32 v[78:79], v[96:97], v[104:105] op_sel_hi:[1,0]
	v_lshl_add_u64 v[76:77], v[102:103], 0, v[60:61]
	v_lshl_add_u64 v[74:75], v[102:103], 0, v[62:63]
	global_load_dwordx4 v[26:29], v[76:77], off nt
	global_load_dwordx4 v[18:21], v[74:75], off nt
	v_pk_mul_f32 v[96:97], v[98:99], v[104:105] op_sel_hi:[1,0]
	v_pk_fma_f32 v[88:89], v[88:89], v[12:13], v[92:93]
	v_pk_fma_f32 v[90:91], v[90:91], v[78:79], v[94:95]
	global_store_dwordx4 v[36:37], v[88:91], off nt
	s_nop 1
	v_mov_b64_e32 v[88:89], v[176:177]
	v_mov_b64_e32 v[90:91], v[178:179]
	s_nop 0
	s_nop 1
	v_mov_b64_e32 v[92:93], v[180:181]
	v_mov_b64_e32 v[94:95], v[182:183]
	v_lshl_add_u64 v[78:79], v[102:103], 0, v[64:65]
	v_lshl_add_u64 v[12:13], v[102:103], 0, v[66:67]
	v_pk_fma_f32 v[8:9], v[88:89], v[8:9], v[92:93]
	v_pk_fma_f32 v[10:11], v[90:91], v[10:11], v[94:95]
	global_store_dwordx4 v[34:35], v[8:11], off nt
	s_nop 1
	v_mov_b64_e32 v[88:89], v[184:185]
	v_mov_b64_e32 v[90:91], v[186:187]
	s_nop 1
	v_mov_b64_e32 v[92:93], v[188:189]
	v_mov_b64_e32 v[94:95], v[190:191]
	s_nop 0
	global_load_dwordx4 v[34:37], v[78:79], off nt
	global_load_dwordx4 v[8:11], v[12:13], off nt
	v_pk_fma_f32 v[88:89], v[88:89], v[96:97], v[92:93]
	v_pk_fma_f32 v[90:91], v[90:91], v[6:7], v[94:95]
	global_store_dwordx4 v[70:71], v[88:91], off nt
	s_nop 1
	v_mov_b64_e32 v[88:89], v[192:193]
	v_mov_b64_e32 v[90:91], v[194:195]
	s_nop 0
	s_nop 1
	v_mov_b64_e32 v[92:93], v[196:197]
	v_mov_b64_e32 v[94:95], v[198:199]
	v_pk_mul_f32 v[6:7], v[100:101], v[104:105] op_sel_hi:[1,0]
	v_pk_fma_f32 v[88:89], v[88:89], v[0:1], v[92:93]
	v_pk_fma_f32 v[90:91], v[90:91], v[6:7], v[94:95]
	global_store_dwordx4 v[68:69], v[88:91], off nt
	s_and_saveexec_b64 s[0:1], vcc
	s_cbranch_execz .LBB0_1624
	s_waitcnt vmcnt(0)
	v_mov_b32_e32 v0, v22
	v_mov_b32_e32 v1, v2
	v_mov_b32_e32 v6, v23
	v_mov_b32_e32 v7, v3
	v_pk_add_f32 v[0:1], v[0:1], v[6:7]
	v_mov_b32_e32 v6, v24
	v_mov_b32_e32 v7, v4
	v_mov_b32_e32 v68, v25
	v_mov_b32_e32 v69, v5
	v_pk_add_f32 v[6:7], v[6:7], v[68:69]
	v_mov_b32_e32 v68, v30
	v_pk_add_f32 v[0:1], v[0:1], v[6:7]
	v_mov_b32_e32 v6, v31
	v_mov_b32_e32 v7, v32
	v_mov_b32_e32 v69, v33
	v_pk_add_f32 v[6:7], v[6:7], v[68:69]
	v_add_f32_e32 v0, 0, v0
	v_pk_add_f32 v[6:7], v[6:7], v[6:7] op_sel:[0,1] op_sel_hi:[1,0]
	v_add_f32_e32 v0, v0, v1
	v_add_f32_e32 v68, v14, v15
	v_add_f32_e32 v70, v16, v17
	v_mov_b32_e32 v1, v26
	v_mov_b32_e32 v7, v27
	v_mov_b32_e32 v69, v28
	v_mov_b32_e32 v71, v29
	v_pk_add_f32 v[0:1], v[0:1], v[6:7]
	v_pk_add_f32 v[6:7], v[68:69], v[70:71]
	v_mov_b32_e32 v68, v18
	v_pk_add_f32 v[0:1], v[0:1], v[6:7]
	v_mov_b32_e32 v6, v19
	v_mov_b32_e32 v7, v20
	v_mov_b32_e32 v69, v21
	v_pk_add_f32 v[6:7], v[6:7], v[68:69]
	v_pk_add_f32 v[0:1], v[0:1], v[0:1] op_sel:[0,1] op_sel_hi:[1,0]
	v_pk_add_f32 v[6:7], v[6:7], v[6:7] op_sel:[0,1] op_sel_hi:[1,0]
	v_add_f32_e32 v68, v34, v35
	v_add_f32_e32 v70, v36, v37
	v_mov_b32_e32 v1, v8
	v_mov_b32_e32 v7, v9
	v_mov_b32_e32 v69, v10
	v_mov_b32_e32 v71, v11
	v_pk_add_f32 v[0:1], v[0:1], v[6:7]
	v_pk_add_f32 v[6:7], v[68:69], v[70:71]
	s_nop 0
	v_pk_add_f32 v[0:1], v[0:1], v[6:7]
	s_nop 0
	v_add_f32_e32 v0, v0, v1
	ds_bpermute_b32 v1, v80, v0
	s_waitcnt lgkmcnt(0)
	v_add_f32_e32 v0, v0, v1
	ds_bpermute_b32 v1, v81, v0
	s_waitcnt lgkmcnt(0)
	v_add_f32_e32 v0, v0, v1
	ds_bpermute_b32 v1, v82, v0
	s_waitcnt lgkmcnt(0)
	v_add_f32_e32 v0, v0, v1
	ds_bpermute_b32 v1, v83, v0
	s_waitcnt lgkmcnt(0)
	v_add_f32_e32 v0, v0, v1
	ds_bpermute_b32 v1, v84, v0
	s_waitcnt lgkmcnt(0)
	v_add_f32_e32 v0, v0, v1
	ds_bpermute_b32 v1, v85, v0
	s_waitcnt lgkmcnt(0)
	v_add_f32_e32 v96, v0, v1
	v_fmamk_f32 v23, v96, 0xba000000, v23
	v_fmamk_f32 v3, v96, 0xba000000, v3
	v_fmamk_f32 v1, v96, 0xba000000, v25
	v_fmac_f32_e32 v22, 0xba000000, v96
	v_fmamk_f32 v69, v96, 0xba000000, v5
	v_fmac_f32_e32 v2, 0xba000000, v96
	v_mov_b32_e32 v6, v23
	v_mov_b32_e32 v7, v3
	v_fmamk_f32 v0, v96, 0xba000000, v24
	v_fmamk_f32 v68, v96, 0xba000000, v4
	v_mov_b32_e32 v4, v22
	v_mov_b32_e32 v5, v2
	v_pk_mul_f32 v[6:7], v[6:7], v[6:7]
	v_mov_b32_e32 v24, v1
	v_mov_b32_e32 v25, v69
	v_pk_fma_f32 v[4:5], v[4:5], v[4:5], v[6:7]
	v_mov_b32_e32 v6, v0
	v_mov_b32_e32 v7, v68
	v_pk_mul_f32 v[24:25], v[24:25], v[24:25]
	v_fmamk_f32 v71, v96, 0xba000000, v31
	v_pk_fma_f32 v[6:7], v[6:7], v[6:7], v[24:25]
	v_fmamk_f32 v70, v96, 0xba000000, v30
	v_pk_add_f32 v[4:5], v[4:5], v[6:7]
	v_fmamk_f32 v33, v96, 0xba000000, v33
	v_fmac_f32_e32 v32, 0xba000000, v96
	v_pk_add_f32 v[4:5], v[4:5], v[4:5] op_sel_hi:[0,1]
	v_pk_mul_f32 v[6:7], v[32:33], v[32:33]
	v_pk_mul_f32 v[24:25], v[70:71], v[70:71]
	v_fmamk_f32 v14, v96, 0xba000000, v14
	v_pk_mov_b32 v[30:31], v[24:25], v[6:7] op_sel:[1,0]
	v_mov_b32_e32 v25, v7
	v_fmamk_f32 v15, v96, 0xba000000, v15
	v_fmac_f32_e32 v16, 0xba000000, v96
	v_mul_f32_e32 v4, v14, v14
	v_pk_add_f32 v[6:7], v[30:31], v[24:25]
	v_fmamk_f32 v17, v96, 0xba000000, v17
	v_pk_fma_f32 v[24:25], v[14:15], v[14:15], v[4:5] op_sel_hi:[1,1,0]
	v_mul_f32_e32 v4, v16, v16
	v_pk_add_f32 v[6:7], v[6:7], v[6:7] op_sel_hi:[0,1]
	v_pk_fma_f32 v[30:31], v[16:17], v[16:17], v[4:5] op_sel_hi:[1,1,0]
	v_fmamk_f32 v89, v96, 0xba000000, v29
	v_fmamk_f32 v88, v96, 0xba000000, v28
	v_fmamk_f32 v27, v96, 0xba000000, v27
	v_fmac_f32_e32 v26, 0xba000000, v96
	v_mul_f32_e32 v24, v26, v26
	v_mul_f32_e32 v30, v27, v27
	v_mul_f32_e32 v6, v88, v88
	v_mul_f32_e32 v4, v89, v89
	v_pk_add_f32 v[24:25], v[24:25], v[30:31]
	v_pk_add_f32 v[4:5], v[6:7], v[4:5]
	v_fmamk_f32 v19, v96, 0xba000000, v19
	v_pk_add_f32 v[24:25], v[24:25], v[4:5]
	s_nop 1
	v_mov_b64_e32 v[4:5], v[132:133]
	v_mov_b64_e32 v[6:7], v[134:135]
	s_nop 1
	v_mov_b64_e32 v[28:29], v[136:137]
	v_mov_b64_e32 v[30:31], v[138:139]
	v_fmamk_f32 v18, v96, 0xba000000, v18
	v_fmamk_f32 v21, v96, 0xba000000, v21
	v_fmac_f32_e32 v20, 0xba000000, v96
	v_pk_add_f32 v[24:25], v[24:25], v[24:25] op_sel_hi:[0,1]
	v_pk_mul_f32 v[90:91], v[20:21], v[20:21]
	v_pk_mul_f32 v[92:93], v[18:19], v[18:19]
	v_fmamk_f32 v34, v96, 0xba000000, v34
	v_pk_mov_b32 v[94:95], v[92:93], v[90:91] op_sel:[1,0]
	v_mov_b32_e32 v93, v91
	v_fmamk_f32 v35, v96, 0xba000000, v35
	v_fmac_f32_e32 v36, 0xba000000, v96
	v_mul_f32_e32 v24, v34, v34
	v_pk_add_f32 v[90:91], v[94:95], v[92:93]
	v_fmamk_f32 v37, v96, 0xba000000, v37
	v_pk_fma_f32 v[92:93], v[34:35], v[34:35], v[24:25] op_sel_hi:[1,1,0]
	v_mul_f32_e32 v24, v36, v36
	v_pk_add_f32 v[90:91], v[90:91], v[90:91] op_sel_hi:[0,1]
	v_pk_fma_f32 v[94:95], v[36:37], v[36:37], v[24:25] op_sel_hi:[1,1,0]
	v_fmamk_f32 v11, v96, 0xba000000, v11
	v_fmamk_f32 v10, v96, 0xba000000, v10
	v_fmamk_f32 v9, v96, 0xba000000, v9
	v_fmac_f32_e32 v8, 0xba000000, v96
	v_mul_f32_e32 v92, v8, v8
	v_mul_f32_e32 v94, v9, v9
	v_mul_f32_e32 v90, v10, v10
	v_mul_f32_e32 v24, v11, v11
	v_pk_add_f32 v[92:93], v[92:93], v[94:95]
	v_pk_add_f32 v[24:25], v[90:91], v[24:25]
	s_nop 0
	v_pk_add_f32 v[24:25], v[92:93], v[24:25]
	s_nop 0
	v_add_f32_e32 v24, v24, v25
	ds_bpermute_b32 v25, v80, v24
	s_waitcnt lgkmcnt(0)
	v_add_f32_e32 v24, v24, v25
	ds_bpermute_b32 v25, v81, v24
	s_waitcnt lgkmcnt(0)
	v_add_f32_e32 v24, v24, v25
	ds_bpermute_b32 v25, v82, v24
	s_waitcnt lgkmcnt(0)
	v_add_f32_e32 v24, v24, v25
	ds_bpermute_b32 v25, v83, v24
	s_waitcnt lgkmcnt(0)
	v_add_f32_e32 v24, v24, v25
	ds_bpermute_b32 v25, v84, v24
	s_waitcnt lgkmcnt(0)
	v_add_f32_e32 v24, v24, v25
	ds_bpermute_b32 v25, v85, v24
	s_waitcnt lgkmcnt(0)
	v_add_f32_e32 v24, v24, v25
	v_fmamk_f32 v24, v24, 0x3a000000, v86
	v_mul_f32_e32 v25, 0x4b800000, v24
	v_cmp_gt_f32_e32 vcc, s7, v24
	s_nop 1
	v_cndmask_b32_e32 v24, v24, v25, vcc
	v_rsq_f32_e32 v24, v24
	s_nop 0
	v_mul_f32_e32 v25, 0x45800000, v24
	v_cndmask_b32_e32 v90, v24, v25, vcc
	v_pk_mul_f32 v[22:23], v[22:23], v[90:91] op_sel_hi:[1,0]
	v_pk_mul_f32 v[0:1], v[0:1], v[90:91] op_sel_hi:[1,0]
	v_pk_fma_f32 v[4:5], v[4:5], v[22:23], v[28:29]
	v_pk_fma_f32 v[6:7], v[6:7], v[0:1], v[30:31]
	global_store_dwordx4 v[72:73], v[4:7], off nt
	s_nop 1
	v_mov_b64_e32 v[4:5], v[140:141]
	v_mov_b64_e32 v[6:7], v[142:143]
	s_nop 0
	s_nop 1
	v_mov_b64_e32 v[22:23], v[144:145]
	v_mov_b64_e32 v[24:25], v[146:147]
	v_pk_mul_f32 v[28:29], v[68:69], v[90:91] op_sel_hi:[1,0]
	v_pk_mul_f32 v[0:1], v[2:3], v[90:91] op_sel_hi:[1,0]
	v_pk_mul_f32 v[16:17], v[16:17], v[90:91] op_sel_hi:[1,0]
	v_pk_mul_f32 v[14:15], v[14:15], v[90:91] op_sel_hi:[1,0]
	v_pk_mul_f32 v[10:11], v[10:11], v[90:91] op_sel_hi:[1,0]
	v_pk_mul_f32 v[8:9], v[8:9], v[90:91] op_sel_hi:[1,0]
	v_pk_fma_f32 v[0:1], v[4:5], v[0:1], v[22:23]
	v_pk_fma_f32 v[2:3], v[6:7], v[28:29], v[24:25]
	global_store_dwordx4 v[72:73], v[0:3], off offset:1024 nt
	s_nop 1
	v_mov_b64_e32 v[0:1], v[148:149]
	v_mov_b64_e32 v[2:3], v[150:151]
	s_nop 0
	s_nop 1
	v_mov_b64_e32 v[4:5], v[156:157]
	v_mov_b64_e32 v[6:7], v[158:159]
	v_pk_mul_f32 v[22:23], v[32:33], v[90:91] op_sel_hi:[1,0]
	v_pk_mul_f32 v[24:25], v[70:71], v[90:91] op_sel_hi:[1,0]
	v_pk_fma_f32 v[2:3], v[2:3], v[22:23], v[6:7]
	v_pk_fma_f32 v[0:1], v[0:1], v[24:25], v[4:5]
	global_store_dwordx4 v[72:73], v[0:3], off offset:2048 nt
	s_nop 1
	v_mov_b64_e32 v[0:1], v[160:161]
	v_mov_b64_e32 v[2:3], v[162:163]
	s_nop 0
	s_nop 1
	v_mov_b64_e32 v[4:5], v[164:165]
	v_mov_b64_e32 v[6:7], v[166:167]
	v_pk_fma_f32 v[0:1], v[0:1], v[14:15], v[4:5]
	v_pk_fma_f32 v[2:3], v[2:3], v[16:17], v[6:7]
	global_store_dwordx4 v[72:73], v[0:3], off offset:3072 nt
	s_nop 1
	v_mov_b64_e32 v[0:1], v[168:169]
	v_mov_b64_e32 v[2:3], v[170:171]
	s_nop 0
	s_nop 1
	v_mov_b64_e32 v[4:5], v[172:173]
	v_mov_b64_e32 v[6:7], v[174:175]
	v_pk_mul_f32 v[14:15], v[88:89], v[90:91] op_sel_hi:[1,0]
	v_pk_mul_f32 v[16:17], v[26:27], v[90:91] op_sel_hi:[1,0]
	v_pk_fma_f32 v[2:3], v[2:3], v[14:15], v[6:7]
	v_pk_fma_f32 v[0:1], v[0:1], v[16:17], v[4:5]
	global_store_dwordx4 v[76:77], v[0:3], off nt
	s_nop 1
	v_mov_b64_e32 v[0:1], v[176:177]
	v_mov_b64_e32 v[2:3], v[178:179]
	s_nop 0
	s_nop 1
	v_mov_b64_e32 v[4:5], v[180:181]
	v_mov_b64_e32 v[6:7], v[182:183]
	v_pk_mul_f32 v[14:15], v[20:21], v[90:91] op_sel_hi:[1,0]
	v_pk_mul_f32 v[16:17], v[18:19], v[90:91] op_sel_hi:[1,0]
	v_pk_fma_f32 v[2:3], v[2:3], v[14:15], v[6:7]
	v_pk_fma_f32 v[0:1], v[0:1], v[16:17], v[4:5]
	global_store_dwordx4 v[74:75], v[0:3], off nt
	s_nop 1
	v_mov_b64_e32 v[0:1], v[184:185]
	v_mov_b64_e32 v[2:3], v[186:187]
	s_nop 0
	s_nop 1
	v_mov_b64_e32 v[4:5], v[188:189]
	v_mov_b64_e32 v[6:7], v[190:191]
	v_pk_mul_f32 v[14:15], v[36:37], v[90:91] op_sel_hi:[1,0]
	v_pk_mul_f32 v[16:17], v[34:35], v[90:91] op_sel_hi:[1,0]
	v_pk_fma_f32 v[2:3], v[2:3], v[14:15], v[6:7]
	v_pk_fma_f32 v[0:1], v[0:1], v[16:17], v[4:5]
	global_store_dwordx4 v[78:79], v[0:3], off nt
	s_nop 1
	v_mov_b64_e32 v[0:1], v[192:193]
	v_mov_b64_e32 v[2:3], v[194:195]
	s_nop 0
	s_nop 1
	v_mov_b64_e32 v[4:5], v[196:197]
	v_mov_b64_e32 v[6:7], v[198:199]
	v_pk_fma_f32 v[0:1], v[0:1], v[8:9], v[4:5]
	v_pk_fma_f32 v[2:3], v[2:3], v[10:11], v[6:7]
	global_store_dwordx4 v[12:13], v[0:3], off nt
	s_branch .LBB0_1624
